# weight conversion of layers 1..3 deferred from the prologue into the cross-attn phase of the previous layer (idle workgroups 128..255 re-enter the prologue item loop)
# speedup vs baseline: 1.0142x; 1.0067x over previous
; #define LAS __attribute__((address_space(3)))
; __global__ void __launch_bounds__(512, 2) mega_fwd(Params P) {
;     extern __shared__ __attribute__((aligned(16))) unsigned char lds_raw[];
;     LAS unsigned char* lds = (LAS unsigned char*)lds_raw;
;     cg::grid_group grid = cg::this_grid();
;     const int G = gridDim.x, bx = blockIdx.x;
;     const int vcu = (G % 8 == 0) ? (bx % 8) * (G / 8) + bx / 8 : bx;
_Z8mega_fwd6Params:
	v_writelane_b32 v255, s0, 60
	v_writelane_b32 v255, s1, 61
	s_mov_b32 s32, 0
	s_mov_b32 s61, 0xbfff
	s_load_dwordx2 s[96:97], s[0:1], 0x110
	s_add_u32 s4, s0, 0x110
	s_addc_u32 s5, s1, 0
	v_writelane_b32 v253, s2, 0
	v_writelane_b32 v253, s2, 1
	s_waitcnt lgkmcnt(0)
	s_and_b32 s3, s96, 7
	s_cmp_lg_u32 s3, 0
	s_cbranch_scc1 .LBB0_2
	v_readlane_b32 s7, v253, 0
	s_ashr_i32 s3, s7, 31
	s_lshr_b32 s3, s3, 29
	s_add_i32 s3, s7, s3
	s_ashr_i32 s6, s3, 3
	s_and_b32 s3, s3, -8
	s_ashr_i32 s2, s96, 3
	s_sub_i32 s3, s7, s3
	s_mul_i32 s2, s2, s3
	s_add_i32 s2, s2, s6
	v_writelane_b32 v253, s2, 1

; #define LAS __attribute__((address_space(3)))
; #define TR_UP(IDX, GIDX, WT, ISUP) { const int kb = r / 88, n0 = (r % 88) * 32; transpose_item(P.in[IDX] + oU, D, DFF, P.in[GIDX] + l * D, WT, (n0 >> 7) * 256 + (n0 & 127) + (ISUP) * 128, scr, kb, n0, lane); return; }
; __device__ __forceinline__ void weight_item(const Params& P, unsigned char* ws, LAS float* scr, int l, int r, int lane) {
;     constexpr int I_UP = WI_UP, I_DN = WI_DN, I_IN = WI_IN, I_SQ = WI_SQ;
;         bf16_t* W1a = (bf16_t*)(ws + WS_W1) + (size_t)(2 * l) * 2 * DFF * D; bf16_t* W1b = W1a + (size_t)2 * DFF * D;
;         bf16_t* WDa = (bf16_t*)(ws + WS_WD) + (size_t)(2 * l) * D * DFF; bf16_t* WDb = WDa + (size_t)D * DFF;
;         const size_t oU = (size_t)l * D * DFF, oS = (size_t)l * D * D;
;     ...
;         if (r < I_UP) TR_UP(10, 9, W1a, 0)
; __device__ __forceinline__ void prologue(const Params& P, LAS unsigned char* lds, int G, int vcu) {
;     ...
;     for (int it = gw; it < NL * W_PER_L; it += NGW) weight_item(P, ws, scr, it / W_PER_L, it % W_PER_L, lane);
.LBB0_10:
	s_add_i32 s48, s48, s60
	s_add_i32 s42, s42, s43
	s_add_i32 s44, s44, s45
	s_cmp_gt_i32 s48, s61
	s_cbranch_scc1 .LBB0_198
.LBB0_11:
	s_mul_hi_i32 s2, s48, 0x2aaaaaab
	s_lshr_b32 s3, s2, 31
	s_ashr_i32 s2, s2, 11
	s_add_i32 s18, s2, s3
	s_mul_i32 s2, s18, 0xffffd000
	s_add_i32 s51, s48, s2
	s_cmp_lg_u32 s32, 0
	s_cbranch_scc1 .Lwd_take
	s_cmp_lg_u32 s96, 0x100
	s_cbranch_scc1 .Lwd_take
	s_cmp_eq_u32 s18, 0
	s_cbranch_scc1 .Lwd_take
	s_cmpk_lt_u32 s51, 0x2c00
	s_cbranch_scc1 .LBB0_10
.Lwd_take:
	s_lshl_b32 s16, s18, 1
	s_mul_i32 s2, s18, 0x1600000
	s_mul_hi_i32 s3, s16, 0xb00000
	s_add_u32 s49, s28, s2
	s_addc_u32 s50, s29, s3
	s_ashr_i32 s19, s18, 31
	s_mul_hi_i32 s21, s18, 0x2c0000
	s_mul_i32 s20, s18, 0x2c0000
	s_cmpk_gt_i32 s51, 0x57f
	s_mov_b64 s[2:3], -1
	s_cbranch_scc0 .LBB0_180
	s_cmpk_gt_u32 s51, 0xaff
	s_cbranch_scc0 .LBB0_161
	s_add_u32 s52, s49, 0xb00000
	s_addc_u32 s53, s50, 0
	s_cmpk_gt_u32 s51, 0x107f
	s_cbranch_scc0 .LBB0_142
	s_cmpk_gt_u32 s51, 0x15ff
	s_cbranch_scc0 .LBB0_123
	s_mul_hi_i32 s2, s16, 0x580000
	s_mul_i32 s16, s16, 0x580000
	s_add_u32 s55, s30, s16
	s_addc_u32 s54, s31, s2
	s_cmpk_gt_u32 s51, 0x1b7f
	s_mov_b64 s[2:3], -1
	s_cbranch_scc0 .LBB0_120
	s_cmpk_gt_u32 s51, 0x20ff
	s_cbranch_scc0 .LBB0_117
	s_cmpk_gt_u32 s51, 0x25ff
	s_cbranch_scc0 .LBB0_98
	s_lshl_b64 s[22:23], s[18:19], 20
	s_add_i32 s16, s51, 0xffffda00
	s_bfe_u32 s56, s51, 0x40005
	s_and_b32 s19, s44, 0x3e0
	s_cmpk_gt_u32 s16, 0x1ff
	s_cbranch_scc0 .LBB0_80
	s_lshr_b32 s16, s16, 9
	s_cmp_lt_i32 s16, 2
	s_cbranch_scc1 .LBB0_61
	s_cmp_lt_i32 s16, 3
	s_cbranch_scc1 .LBB0_58
	s_mov_b64 s[24:25], -1
	s_cmp_lg_u32 s16, 3
	v_cmp_ne_u32_e64 s[2:3], 1, v55
	s_cbranch_scc0 .LBB0_39
	s_load_dwordx16 s[64:79], s[0:1], 0xc0
	s_lshl_b64 s[24:25], s[22:23], 2
	v_mov_b32_e32 v43, v37
	v_mov_b32_e32 v44, 1.0
	v_mov_b32_e32 v46, 1.0
	s_waitcnt lgkmcnt(0)
	s_add_u32 s57, s66, s24
	s_addc_u32 s59, s67, s25
	s_load_dwordx16 s[64:79], s[0:1], 0x80
	s_lshl_b32 s24, s18, 10
	s_ashr_i32 s25, s24, 31
	s_lshl_b64 s[24:25], s[24:25], 2
	s_waitcnt lgkmcnt(0)
	s_add_u32 s24, s76, s24
	s_addc_u32 s25, s77, s25
	s_lshl_b32 s16, s56, 6
	s_lshl_b32 s58, s19, 2
	s_add_u32 s58, s57, s58
	v_or_b32_e32 v32, s16, v1
	s_addc_u32 s59, s59, 0
	v_lshl_add_u64 v[30:31], s[58:59], 0, v[42:43]
	v_lshlrev_b32_e32 v36, 12, v32
	v_lshl_add_u64 v[2:3], v[30:31], 0, v[36:37]
	global_load_dwordx4 v[2:5], v[2:3], off
	s_and_b64 vcc, exec, s[2:3]
	v_lshlrev_b32_e32 v43, 2, v32
	s_cbranch_vccnz .LBB0_24
	global_load_dword v46, v43, s[24:25]

; __device__ __forceinline__ void prologue(const Params& P, LAS unsigned char* lds, int G, int vcu) {
;     ...
;     float* X = (float*)(ws + WS_X); bf16_t* XB = (bf16_t*)(ws + WS_XB); float* SS = (float*)(ws + WS_SS);
;     for (int m = gw; m < T + 512; m += NGW) {
;         const bool ismem = m >= T;
;         const float* xp0 = P.in[0]; const float* xs0 = P.in[1]; const float* mp0 = P.in[2];
;         const float* src = ismem ? mp0 + (size_t)(m - T) * D : (m < TP ? xp0 + (size_t)m * D : xs0 + (size_t)(m - TP) * D);
;         f32x4 v[4]; float ss = 0.f;
; #pragma unroll
;         for (int j = 0; j < 4; ++j) { v[j] = ((const f32x4*)src)[lane + 64 * j]; ss += (v[j][0] * v[j][0] + v[j][1] * v[j][1]) + (v[j][2] * v[j][2] + v[j][3] * v[j][3]); }
;         ss = wave_sum(ss);
.LBB0_198:
	s_cmp_lg_u32 s32, 0
	s_cbranch_scc1 .Lwd_return
	s_load_dwordx16 s[8:23], s[0:1], 0x0
	s_cmpk_gt_i32 s26, 0x43ff
	v_mbcnt_lo_u32_b32 v10, -1, 0
	s_waitcnt lgkmcnt(0)
	v_writelane_b32 v253, s8, 55
	s_nop 1
	v_writelane_b32 v253, s9, 56
	v_writelane_b32 v253, s10, 57
	v_writelane_b32 v254, s17, 0
	v_writelane_b32 v253, s11, 58
	v_writelane_b32 v254, s18, 1
	v_writelane_b32 v253, s12, 59
	v_writelane_b32 v254, s19, 2
	v_writelane_b32 v253, s13, 60
	v_writelane_b32 v254, s20, 3
	v_writelane_b32 v253, s14, 61
	v_writelane_b32 v254, s21, 4
	v_writelane_b32 v253, s15, 62
	v_writelane_b32 v254, s22, 5
	v_writelane_b32 v253, s16, 63
	v_writelane_b32 v254, s23, 6
	s_cbranch_scc1 .LBB0_210
	v_mbcnt_hi_u32_b32 v6, -1, v10
	v_and_b32_e32 v1, 64, v6
	v_add_u32_e32 v7, 64, v1
	v_xor_b32_e32 v1, 1, v6
	v_cmp_lt_i32_e32 vcc, v1, v7
	v_xor_b32_e32 v2, 2, v6
	v_xor_b32_e32 v3, 4, v6
	v_cndmask_b32_e32 v1, v6, v1, vcc
	v_cmp_lt_i32_e32 vcc, v2, v7
	v_xor_b32_e32 v4, 8, v6
	v_xor_b32_e32 v5, 16, v6
	v_cndmask_b32_e32 v2, v6, v2, vcc
	v_cmp_lt_i32_e32 vcc, v3, v7
	v_xor_b32_e32 v8, 32, v6
	s_ashr_i32 s6, s27, 31
	v_cndmask_b32_e32 v3, v6, v3, vcc
	v_cmp_lt_i32_e32 vcc, v4, v7
	s_ashr_i32 s9, s62, 31
	s_add_u32 s8, s27, s62
	v_cndmask_b32_e32 v4, v6, v4, vcc
	v_cmp_lt_i32_e32 vcc, v5, v7
	s_mov_b32 s7, 0
	v_lshlrev_b32_e32 v1, 2, v1
	v_cndmask_b32_e32 v5, v6, v5, vcc
	v_cmp_lt_i32_e32 vcc, v8, v7
	v_lshlrev_b32_e32 v2, 2, v2
	v_lshlrev_b32_e32 v3, 2, v3
	v_cndmask_b32_e32 v6, v6, v8, vcc
	v_lshlrev_b32_e32 v4, 2, v4
	v_lshlrev_b32_e32 v5, 2, v5
	v_lshlrev_b32_e32 v6, 2, v6
	v_cmp_gt_u32_e64 s[0:1], 16, v34
	v_cmp_eq_u32_e64 s[2:3], 0, v34
	s_addc_u32 s9, s6, s9
	s_ashr_i32 s20, s60, 31
	v_lshlrev_b32_e32 v7, 4, v34
	v_lshlrev_b32_e32 v8, 3, v34
	v_lshlrev_b32_e32 v9, 2, v34
	s_branch .LBB0_201

; #define LAS __attribute__((address_space(3)))
; __device__ __forceinline__ void weights_deferred(const Params& P, LAS unsigned char* lds, int l, int part, int nparts) {
;     int tid = threadIdx.x; asm volatile("" : "+v"(tid));
;     const int lane = tid & 63, wave = __builtin_amdgcn_readfirstlane(tid >> 6);
;     LAS float* scr = (LAS float*)(lds + wave * 16384);
;     for (int r = part * NW + wave; r < W_NOKV; r += nparts * NW) weight_item(P, P.ws, scr, l, r, lane);
; }
; __device__ __forceinline__ void prologue(const Params& P, LAS unsigned char* lds, int G, int vcu) {
;     int tid = threadIdx.x; asm volatile("" : "+v"(tid));
;     const int lane = tid & 63, wave = __builtin_amdgcn_readfirstlane(tid >> 6);
;     LAS float* scr = (LAS float*)(lds + wave * 16384);
;     unsigned char* ws = P.ws;
;     const int gw = vcu * NW + wave, NGW = G * NW;
;     for (int it = gw; it < NL * W_PER_L; it += NGW) weight_item(P, ws, scr, it / W_PER_L, it % W_PER_L, lane);
.Lwd_check:
	s_cmp_gt_u32 s88, 2
	s_cbranch_scc1 .LBB0_596
	s_cmp_lg_u32 s96, 0x100
	s_cbranch_scc1 .LBB0_596
	v_writelane_b32 v250, s0, 0
	v_writelane_b32 v250, s1, 1
	v_writelane_b32 v250, s2, 2
	v_writelane_b32 v250, s3, 3
	v_writelane_b32 v250, s4, 4
	v_writelane_b32 v250, s5, 5
	v_writelane_b32 v250, s6, 6
	v_writelane_b32 v250, s7, 7
	v_writelane_b32 v250, s8, 8
	v_writelane_b32 v250, s9, 9
	v_writelane_b32 v250, s10, 10
	v_writelane_b32 v250, s11, 11
	v_writelane_b32 v250, s12, 12
	v_writelane_b32 v250, s13, 13
	v_writelane_b32 v250, s14, 14
	v_writelane_b32 v250, s15, 15
	v_writelane_b32 v250, s16, 16
	v_writelane_b32 v250, s17, 17
	v_writelane_b32 v250, s18, 18
	v_writelane_b32 v250, s19, 19
	v_writelane_b32 v250, s20, 20
	v_writelane_b32 v250, s21, 21
	v_writelane_b32 v250, s22, 22
	v_writelane_b32 v250, s23, 23
	v_writelane_b32 v250, s24, 24
	v_writelane_b32 v250, s25, 25
	v_writelane_b32 v250, s26, 26
	v_writelane_b32 v250, s27, 27
	v_writelane_b32 v250, s28, 28
	v_writelane_b32 v250, s29, 29
	v_writelane_b32 v250, s30, 30
	v_writelane_b32 v250, s31, 31
	v_writelane_b32 v250, s32, 32
	v_writelane_b32 v250, s33, 33
	v_writelane_b32 v250, s34, 34
	v_writelane_b32 v250, s35, 35
	v_writelane_b32 v250, s36, 36
	v_writelane_b32 v250, s37, 37
	v_writelane_b32 v250, s38, 38
	v_writelane_b32 v250, s39, 39
	v_writelane_b32 v250, s40, 40
	v_writelane_b32 v250, s41, 41
	v_writelane_b32 v250, s42, 42
	v_writelane_b32 v250, s43, 43
	v_writelane_b32 v250, s44, 44
	v_writelane_b32 v250, s45, 45
	v_writelane_b32 v250, s46, 46
	v_writelane_b32 v250, s47, 47
	v_writelane_b32 v250, s48, 48
	v_writelane_b32 v250, s49, 49
	v_writelane_b32 v250, s50, 50
	v_writelane_b32 v250, s51, 51
	v_writelane_b32 v250, s52, 52
	v_writelane_b32 v250, s53, 53
	v_writelane_b32 v250, s54, 54
	v_writelane_b32 v250, s55, 55
	v_writelane_b32 v250, s56, 56
	v_writelane_b32 v250, s57, 57
	v_writelane_b32 v250, s58, 58
	v_writelane_b32 v250, s59, 59
	v_writelane_b32 v250, s60, 60
	v_writelane_b32 v250, s61, 61
	v_writelane_b32 v250, s62, 62
	v_writelane_b32 v250, s63, 63
	v_writelane_b32 v251, s64, 0
	v_writelane_b32 v251, s65, 1
	v_writelane_b32 v251, s66, 2
	v_writelane_b32 v251, s67, 3
	v_writelane_b32 v251, s68, 4
	v_writelane_b32 v251, s69, 5
	v_writelane_b32 v251, s70, 6
	v_writelane_b32 v251, s71, 7
	v_writelane_b32 v251, s72, 8
	v_writelane_b32 v251, s73, 9
	v_writelane_b32 v251, s74, 10
	v_writelane_b32 v251, s75, 11
	v_writelane_b32 v251, s76, 12
	v_writelane_b32 v251, s77, 13
	v_writelane_b32 v251, s78, 14
	v_writelane_b32 v251, s79, 15
	v_readlane_b32 s0, v255, 60
	v_readlane_b32 s1, v255, 61
	v_mov_b32_e32 v1, v208
	s_mov_b32 s32, 1
	s_movk_i32 s60, 0x400
	v_readfirstlane_b32 s2, v1
	v_and_b32_e32 v34, 63, v1
	s_ashr_i32 s27, s2, 6
	s_add_i32 s2, s88, 1
	s_mul_i32 s2, s2, 0x3000
	s_add_i32 s3, s68, 0xffffff80
	s_lshl_b32 s3, s3, 3
	s_add_i32 s61, s2, 0x2bff
	s_add_i32 s26, s2, s3
	s_add_i32 s26, s26, s27
	s_lshl_b32 s2, s27, 14
	s_add_i32 s6, s2, 0
	s_add_u32 s28, s94, 0x18000000
	s_addc_u32 s29, s95, 0
	s_add_u32 s30, s94, 0x1d800000
	s_addc_u32 s31, s95, 0
	s_add_u32 s34, s94, 0x22800000
	s_addc_u32 s35, s95, 0
	s_add_u32 s36, s94, 0x22000000
	s_addc_u32 s37, s95, 0
	s_load_dwordx16 s[8:23], s[0:1], 0x80
	s_add_u32 s38, s94, 0x21800000
	s_addc_u32 s39, s95, 0
	v_and_b32_e32 v3, 7, v1
	s_add_u32 s40, s94, 0x20400000
	s_load_dwordx16 s[44:59], s[0:1], 0x40
	v_mov_b32_e32 v37, 0
	v_lshlrev_b32_e32 v36, 4, v3
	s_addc_u32 s41, s95, 0
	s_load_dwordx16 s[64:79], s[0:1], 0xc0
	v_lshrrev_b32_e32 v1, 3, v34
	v_lshl_add_u64 v[4:5], s[94:95], 0, v[36:37]
	s_mov_b64 s[2:3], 0x23000000
	s_waitcnt lgkmcnt(0)
	s_cmp_lg_u64 s[20:21], 0
	v_lshlrev_b32_e32 v2, 2, v3
	v_lshlrev_b32_e32 v38, 3, v3
	v_mul_u32_u24_e32 v3, 0x420, v3
	v_lshl_add_u64 v[40:41], v[4:5], 0, s[2:3]
	v_lshlrev_b32_e32 v4, 2, v1
	s_cselect_b64 s[2:3], -1, 0
	s_cmp_lg_u64 s[18:19], 0
	v_add_u32_e32 v35, s6, v36
	v_add3_u32 v53, s6, v3, v4
	s_cselect_b64 s[6:7], -1, 0
	s_cmp_lg_u64 s[14:15], 0
	s_cselect_b64 s[8:9], -1, 0
	s_cmp_lg_u64 s[54:55], 0
	s_cselect_b64 s[10:11], -1, 0
	s_cmp_lg_u64 s[70:71], 0
	s_cselect_b64 s[12:13], -1, 0
	s_cmp_lg_u64 s[46:47], 0
	v_mul_u32_u24_e32 v39, 0x84, v1
	v_or_b32_e32 v45, 8, v1
	v_or_b32_e32 v47, 16, v1
	v_or_b32_e32 v51, 24, v1
	v_cndmask_b32_e64 v55, 0, 1, s[2:3]
	v_lshlrev_b32_e32 v42, 2, v2
	v_mov_b32_e32 v57, 0x8000
	v_mov_b32_e32 v59, 0x10000
	v_mov_b32_e32 v60, 0x18000
	v_mov_b32_e32 v61, 0x20000
	v_mov_b32_e32 v62, 0x28000
	v_mov_b32_e32 v63, 0x30000
	v_mov_b32_e32 v64, 0x38000
	s_cselect_b64 s[14:15], -1, 0
	s_lshl_b32 s42, s26, 1
	s_lshl_b32 s43, s60, 1
	s_lshl_b32 s44, s26, 5
	s_lshl_b32 s45, s60, 5
	s_movk_i32 s46, 0x2800
	s_movk_i32 s47, 0x2c00
	s_mov_b32 s48, s26
	s_mov_b32 s17, 0
	s_branch .LBB0_11
; #define LAS __attribute__((address_space(3)))
; __device__ __forceinline__ void weights_deferred(const Params& P, LAS unsigned char* lds, int l, int part, int nparts) {
;     int tid = threadIdx.x; asm volatile("" : "+v"(tid));
;     const int lane = tid & 63, wave = __builtin_amdgcn_readfirstlane(tid >> 6);
;     LAS float* scr = (LAS float*)(lds + wave * 16384);
;     for (int r = part * NW + wave; r < W_NOKV; r += nparts * NW) weight_item(P, P.ws, scr, l, r, lane);
; }
.Lwd_return:
	v_mov_b32_e32 v1, 0
	v_readlane_b32 s0, v250, 0
	v_readlane_b32 s1, v250, 1
	v_readlane_b32 s2, v250, 2
	v_readlane_b32 s3, v250, 3
	v_readlane_b32 s4, v250, 4
	v_readlane_b32 s5, v250, 5
	v_readlane_b32 s6, v250, 6
	v_readlane_b32 s7, v250, 7
	v_readlane_b32 s8, v250, 8
	v_readlane_b32 s9, v250, 9
	v_readlane_b32 s10, v250, 10
	v_readlane_b32 s11, v250, 11
	v_readlane_b32 s12, v250, 12
	v_readlane_b32 s13, v250, 13
	v_readlane_b32 s14, v250, 14
	v_readlane_b32 s15, v250, 15
	v_readlane_b32 s16, v250, 16
	v_readlane_b32 s17, v250, 17
	v_readlane_b32 s18, v250, 18
	v_readlane_b32 s19, v250, 19
	v_readlane_b32 s20, v250, 20
	v_readlane_b32 s21, v250, 21
	v_readlane_b32 s22, v250, 22
	v_readlane_b32 s23, v250, 23
	v_readlane_b32 s24, v250, 24
	v_readlane_b32 s25, v250, 25
	v_readlane_b32 s26, v250, 26
	v_readlane_b32 s27, v250, 27
	v_readlane_b32 s28, v250, 28
	v_readlane_b32 s29, v250, 29
	v_readlane_b32 s30, v250, 30
	v_readlane_b32 s31, v250, 31
	v_readlane_b32 s32, v250, 32
	v_readlane_b32 s33, v250, 33
	v_readlane_b32 s34, v250, 34
	v_readlane_b32 s35, v250, 35
	v_readlane_b32 s36, v250, 36
	v_readlane_b32 s37, v250, 37
	v_readlane_b32 s38, v250, 38
	v_readlane_b32 s39, v250, 39
	v_readlane_b32 s40, v250, 40
	v_readlane_b32 s41, v250, 41
	v_readlane_b32 s42, v250, 42
	v_readlane_b32 s43, v250, 43
	v_readlane_b32 s44, v250, 44
	v_readlane_b32 s45, v250, 45
	v_readlane_b32 s46, v250, 46
	v_readlane_b32 s47, v250, 47
	v_readlane_b32 s48, v250, 48
	v_readlane_b32 s49, v250, 49
	v_readlane_b32 s50, v250, 50
	v_readlane_b32 s51, v250, 51
	v_readlane_b32 s52, v250, 52
	v_readlane_b32 s53, v250, 53
	v_readlane_b32 s54, v250, 54
	v_readlane_b32 s55, v250, 55
	v_readlane_b32 s56, v250, 56
	v_readlane_b32 s57, v250, 57
	v_readlane_b32 s58, v250, 58
	v_readlane_b32 s59, v250, 59
	v_readlane_b32 s60, v250, 60
	v_readlane_b32 s61, v250, 61
	v_readlane_b32 s62, v250, 62
	v_readlane_b32 s63, v250, 63
	v_readlane_b32 s64, v251, 0
	v_readlane_b32 s65, v251, 1
	v_readlane_b32 s66, v251, 2
	v_readlane_b32 s67, v251, 3
	v_readlane_b32 s68, v251, 4
	v_readlane_b32 s69, v251, 5
	v_readlane_b32 s70, v251, 6
	v_readlane_b32 s71, v251, 7
	v_readlane_b32 s72, v251, 8
	v_readlane_b32 s73, v251, 9
	v_readlane_b32 s74, v251, 10
	v_readlane_b32 s75, v251, 11
	v_readlane_b32 s76, v251, 12
	v_readlane_b32 s77, v251, 13
	v_readlane_b32 s78, v251, 14
	v_readlane_b32 s79, v251, 15
	s_branch .LBB0_596
